# RS4+prio+V4 with packs hoisted before the rare-path branch and the scale ops inside the MFMA->VALU distance
# speedup vs baseline: 1.0293x; 1.0038x over previous
.LBB0_538:
	s_add_i32 s2, s79, -1
	s_min_u32 s85, s2, s84
	s_lshl_b32 s4, s85, 6
	s_cmp_lt_u32 s85, 4
	s_cselect_b64 s[2:3], -1, 0
	s_add_i32 s88, s4, 0xffffff00
	s_and_b64 s[86:87], s[2:3], exec
	s_cselect_b32 s4, s4, s88
	s_cselect_b32 s88, s17, s73
	s_cselect_b32 s89, s16, s72
	s_lshl_b64 s[86:87], s[4:5], 7
	s_add_u32 s86, s89, s86
	s_addc_u32 s87, s88, s87
	s_lshl_b32 s88, s85, 1
	s_mov_b32 s89, s5
	s_lshl_b64 s[88:89], s[88:89], 2
	s_add_u32 s85, s18, s88
	s_addc_u32 s90, s19, s89
	s_add_u32 s88, s74, s88
	s_addc_u32 s89, s75, s89
	s_add_u32 s88, s88, 0xffffffe0
	s_addc_u32 s89, s89, -1
	s_and_b64 s[2:3], s[2:3], exec
	s_cselect_b32 s3, s90, s89
	s_cselect_b32 s2, s85, s88
	s_waitcnt vmcnt(0) lgkmcnt(0)
	s_barrier
	s_setprio 1
	s_waitcnt vmcnt(0)
	global_load_dwordx2 v[208:209], v201, s[2:3]
	s_cselect_b32 s85, s21, s77
	s_cselect_b32 s88, s20, s76
	s_lshl_b64 s[2:3], s[4:5], 9
	s_add_u32 s2, s88, s2
	ds_read_b128 v[180:183], v225
	ds_read_b128 v[184:187], v226
	s_addc_u32 s3, s85, s3
	s_cmp_lg_u32 0, -1
	s_cselect_b32 s4, 0, 0
	s_add_i32 s85, s4, s80
	s_add_i32 s4, s4, s81
	s_addk_i32 s85, 0x4000
	s_add_i32 s88, s4, 0x10000
	s_waitcnt lgkmcnt(1)
	v_mfma_i32_32x32x32_i8 v[148:163], v[180:183], v[164:167], v[132:147]
	ds_read_b128 v[180:183], v227
	s_waitcnt lgkmcnt(1)
	v_mfma_i32_32x32x32_i8 v[148:163], v[184:187], v[168:171], v[148:163]
	ds_read_b128 v[188:191], v228
	s_waitcnt lgkmcnt(1)
	v_mfma_i32_32x32x32_i8 v[148:163], v[180:183], v[172:175], v[148:163]
	ds_read_b64_tr_b16 v[184:185], v3 offset:32768
	ds_read_b64_tr_b16 v[186:187], v3 offset:36864
	s_waitcnt lgkmcnt(2)
	v_mfma_i32_32x32x32_i8 v[148:163], v[188:191], v[176:179], v[148:163]
	ds_read_b64_tr_b16 v[180:181], v3 offset:33280
	ds_read_b64_tr_b16 v[182:183], v3 offset:37376
	s_nop 7
	v_mul_f32_e32 v189, v221, v206
	v_fma_f32 v190, s100, v189, v255
	v_fma_f32 v148, v148, v189, -v190
	v_fma_f32 v149, v149, v189, -v190
	v_exp_f32_e32 v148, v148
	v_fma_f32 v150, v150, v189, -v190
	v_exp_f32_e32 v149, v149
	v_fma_f32 v151, v151, v189, -v190
	v_exp_f32_e32 v150, v150
	v_fma_f32 v152, v152, v189, -v190
	v_exp_f32_e32 v151, v151
	v_fma_f32 v153, v153, v189, -v190
	v_exp_f32_e32 v152, v152
	v_fma_f32 v154, v154, v189, -v190
	v_exp_f32_e32 v153, v153
	v_fma_f32 v155, v155, v189, -v190
	v_exp_f32_e32 v154, v154
	v_fma_f32 v156, v156, v189, -v190
	v_exp_f32_e32 v155, v155
	v_fma_f32 v157, v157, v189, -v190
	v_exp_f32_e32 v156, v156
	v_fma_f32 v158, v158, v189, -v190
	v_exp_f32_e32 v157, v157
	v_fma_f32 v159, v159, v189, -v190
	v_exp_f32_e32 v158, v158
	v_fma_f32 v160, v160, v189, -v190
	v_exp_f32_e32 v159, v159
	v_fma_f32 v161, v161, v189, -v190
	v_exp_f32_e32 v160, v160
	v_fma_f32 v162, v162, v189, -v190
	v_exp_f32_e32 v161, v161
	v_fma_f32 v163, v163, v189, -v190
	v_exp_f32_e32 v162, v162
	v_exp_f32_e32 v163, v163
	v_add_f32_e32 v188, v148, v149
	v_add_f32_e32 v189, v150, v151
	v_add_f32_e32 v190, v152, v153
	v_add_f32_e32 v191, v154, v155
	v_add_f32_e32 v192, v156, v157
	v_add_f32_e32 v193, v158, v159
	v_add_f32_e32 v194, v160, v161
	v_add_f32_e32 v195, v162, v163
	v_add_f32_e32 v188, v188, v189
	v_add_f32_e32 v190, v190, v191
	v_add_f32_e32 v192, v192, v193
	v_add_f32_e32 v194, v194, v195
	v_add_f32_e32 v188, v188, v190
	v_add_f32_e32 v192, v192, v194
	v_add_f32_e32 v188, v188, v192
	v_cmp_lt_f32_e32 vcc, s101, v188
	v_cvt_pk_bf16_f32 v155, v154, v155
	v_cvt_pk_bf16_f32 v154, v152, v153
	v_cvt_pk_bf16_f32 v152, v148, v149
	v_cvt_pk_bf16_f32 v153, v150, v151
	v_cvt_pk_bf16_f32 v148, v156, v157
	v_cvt_pk_bf16_f32 v149, v158, v159
	v_cvt_pk_bf16_f32 v150, v160, v161
	v_cvt_pk_bf16_f32 v151, v162, v163
	s_cbranch_vccnz .Lv4_rare_h1
.Lv4_cont_h1:
	v_add_f32_e32 v224, v224, v188
	s_barrier
	s_setprio 0
	s_waitcnt lgkmcnt(2)
	v_mfma_f32_32x32x16_bf16 v[4:19], v[152:155], v[184:187], v[4:19]
	ds_read_b64_tr_b16 v[156:157], v3 offset:33792
	ds_read_b64_tr_b16 v[158:159], v3 offset:37888
	s_waitcnt lgkmcnt(2)
	v_mfma_f32_32x32x16_bf16 v[116:131], v[152:155], v[180:183], v[116:131]
	ds_read_b64_tr_b16 v[160:161], v3 offset:34304
	ds_read_b64_tr_b16 v[162:163], v3 offset:38400
	s_add_i32 m0, s80, 0x4000
	s_nop 0
	global_load_lds_dwordx4 v200, s[86:87]
	s_waitcnt lgkmcnt(2)
	v_mfma_f32_32x32x16_bf16 v[100:115], v[152:155], v[156:159], v[100:115]
	ds_read_b64_tr_b16 v[156:157], v3 offset:34816
	ds_read_b64_tr_b16 v[158:159], v3 offset:38912
	s_waitcnt lgkmcnt(2)
	v_mfma_f32_32x32x16_bf16 v[84:99], v[152:155], v[160:163], v[84:99]
	ds_read_b64_tr_b16 v[160:161], v3 offset:35328
	ds_read_b64_tr_b16 v[162:163], v3 offset:39424
	s_add_i32 m0, s81, 0x10000
	s_nop 0
	global_load_lds_dwordx4 v204, s[2:3]
	s_waitcnt lgkmcnt(2)
	v_mfma_f32_32x32x16_bf16 v[68:83], v[152:155], v[156:159], v[68:83]
	ds_read_b64_tr_b16 v[156:157], v3 offset:35840
	ds_read_b64_tr_b16 v[158:159], v3 offset:39936
	s_waitcnt lgkmcnt(2)
	v_mfma_f32_32x32x16_bf16 v[52:67], v[152:155], v[160:163], v[52:67]
	ds_read_b64_tr_b16 v[160:161], v3 offset:36352
	ds_read_b64_tr_b16 v[162:163], v3 offset:40448
	s_add_u32 s2, s2, 0x80
	s_addc_u32 s3, s3, 0
	s_add_i32 m0, s81, 0x10400
	s_nop 0
	global_load_lds_dwordx4 v204, s[2:3]
	s_waitcnt lgkmcnt(2)
	v_mfma_f32_32x32x16_bf16 v[36:51], v[152:155], v[156:159], v[36:51]
	ds_read_b64_tr_b16 v[156:157], v3 offset:40960
	ds_read_b64_tr_b16 v[158:159], v3 offset:45056
	s_waitcnt lgkmcnt(2)
	v_mfma_f32_32x32x16_bf16 v[20:35], v[152:155], v[160:163], v[20:35]
	ds_read_b64_tr_b16 v[152:153], v3 offset:41472
	ds_read_b64_tr_b16 v[154:155], v3 offset:45568
	s_add_u32 s2, s2, 0x80
	s_addc_u32 s3, s3, 0
	s_add_i32 m0, s81, 0x10800
	s_nop 0
	global_load_lds_dwordx4 v204, s[2:3]
	s_waitcnt lgkmcnt(2)
	v_mfma_f32_32x32x16_bf16 v[4:19], v[148:151], v[156:159], v[4:19]
	ds_read_b64_tr_b16 v[156:157], v3 offset:41984
	ds_read_b64_tr_b16 v[158:159], v3 offset:46080
	s_waitcnt lgkmcnt(2)
	v_mfma_f32_32x32x16_bf16 v[116:131], v[148:151], v[152:155], v[116:131]
	ds_read_b64_tr_b16 v[152:153], v3 offset:42496
	ds_read_b64_tr_b16 v[154:155], v3 offset:46592
	s_add_u32 s2, s2, 0x80
	s_addc_u32 s3, s3, 0
	s_add_i32 m0, s81, 0x10c00
	s_nop 0
	global_load_lds_dwordx4 v204, s[2:3]
	s_waitcnt lgkmcnt(2)
	v_mfma_f32_32x32x16_bf16 v[100:115], v[148:151], v[156:159], v[100:115]
	ds_read_b64_tr_b16 v[156:157], v3 offset:43008
	ds_read_b64_tr_b16 v[158:159], v3 offset:47104
	s_waitcnt lgkmcnt(2)
	v_mfma_f32_32x32x16_bf16 v[84:99], v[148:151], v[152:155], v[84:99]
	ds_read_b64_tr_b16 v[152:153], v3 offset:43520
	ds_read_b64_tr_b16 v[154:155], v3 offset:47616
	s_waitcnt lgkmcnt(2)
	v_mfma_f32_32x32x16_bf16 v[68:83], v[148:151], v[156:159], v[68:83]
	ds_read_b64_tr_b16 v[156:157], v3 offset:44032
	ds_read_b64_tr_b16 v[158:159], v3 offset:48128
	s_waitcnt lgkmcnt(2)
	v_mfma_f32_32x32x16_bf16 v[52:67], v[148:151], v[152:155], v[52:67]
	ds_read_b64_tr_b16 v[152:153], v3 offset:44544
	ds_read_b64_tr_b16 v[154:155], v3 offset:48640
	s_waitcnt lgkmcnt(2)
	v_mfma_f32_32x32x16_bf16 v[36:51], v[148:151], v[156:159], v[36:51]
	s_waitcnt lgkmcnt(0)
	v_mfma_f32_32x32x16_bf16 v[20:35], v[148:151], v[152:155], v[20:35]
	s_barrier
	s_setprio 1
	ds_read_b128 v[180:183], v225 offset:4096
	ds_read_b128 v[184:187], v226 offset:4096
	s_waitcnt lgkmcnt(1)
	v_mfma_i32_32x32x32_i8 v[148:163], v[180:183], v[164:167], v[132:147]
	ds_read_b128 v[180:183], v227 offset:4096
	s_waitcnt lgkmcnt(1)
	v_mfma_i32_32x32x32_i8 v[148:163], v[184:187], v[168:171], v[148:163]
	ds_read_b128 v[188:191], v228 offset:4096
	s_waitcnt lgkmcnt(1)
	v_mfma_i32_32x32x32_i8 v[148:163], v[180:183], v[172:175], v[148:163]
	ds_read_b64_tr_b16 v[184:185], v3 offset:49152
	ds_read_b64_tr_b16 v[186:187], v3 offset:53248
	s_waitcnt lgkmcnt(2)
	v_mfma_i32_32x32x32_i8 v[148:163], v[188:191], v[176:179], v[148:163]
	ds_read_b64_tr_b16 v[180:181], v3 offset:49664
	ds_read_b64_tr_b16 v[182:183], v3 offset:53760
	s_nop 7
	v_mul_f32_e32 v189, v221, v207
	v_fma_f32 v190, s100, v189, v255
	v_fma_f32 v148, v148, v189, -v190
	v_fma_f32 v149, v149, v189, -v190
	v_exp_f32_e32 v148, v148
	v_fma_f32 v150, v150, v189, -v190
	v_exp_f32_e32 v149, v149
	v_fma_f32 v151, v151, v189, -v190
	v_exp_f32_e32 v150, v150
	v_fma_f32 v152, v152, v189, -v190
	v_exp_f32_e32 v151, v151
	v_fma_f32 v153, v153, v189, -v190
	v_exp_f32_e32 v152, v152
	v_fma_f32 v154, v154, v189, -v190
	v_exp_f32_e32 v153, v153
	v_fma_f32 v155, v155, v189, -v190
	v_exp_f32_e32 v154, v154
	v_fma_f32 v156, v156, v189, -v190
	v_exp_f32_e32 v155, v155
	v_fma_f32 v157, v157, v189, -v190
	v_exp_f32_e32 v156, v156
	v_fma_f32 v158, v158, v189, -v190
	v_exp_f32_e32 v157, v157
	v_fma_f32 v159, v159, v189, -v190
	v_exp_f32_e32 v158, v158
	v_fma_f32 v160, v160, v189, -v190
	v_exp_f32_e32 v159, v159
	v_fma_f32 v161, v161, v189, -v190
	v_exp_f32_e32 v160, v160
	v_fma_f32 v162, v162, v189, -v190
	v_exp_f32_e32 v161, v161
	v_fma_f32 v163, v163, v189, -v190
	v_exp_f32_e32 v162, v162
	v_exp_f32_e32 v163, v163
	v_add_f32_e32 v188, v148, v149
	v_add_f32_e32 v189, v150, v151
	v_add_f32_e32 v190, v152, v153
	v_add_f32_e32 v191, v154, v155
	v_add_f32_e32 v192, v156, v157
	v_add_f32_e32 v193, v158, v159
	v_add_f32_e32 v194, v160, v161
	v_add_f32_e32 v195, v162, v163
	v_add_f32_e32 v188, v188, v189
	v_add_f32_e32 v190, v190, v191
	v_add_f32_e32 v192, v192, v193
	v_add_f32_e32 v194, v194, v195
	v_add_f32_e32 v188, v188, v190
	v_add_f32_e32 v192, v192, v194
	v_add_f32_e32 v188, v188, v192
	v_cmp_lt_f32_e32 vcc, s101, v188
	v_cvt_pk_bf16_f32 v155, v154, v155
	v_cvt_pk_bf16_f32 v154, v152, v153
	v_cvt_pk_bf16_f32 v152, v148, v149
	v_cvt_pk_bf16_f32 v153, v150, v151
	v_cvt_pk_bf16_f32 v148, v156, v157
	v_cvt_pk_bf16_f32 v149, v158, v159
	v_cvt_pk_bf16_f32 v150, v160, v161
	v_cvt_pk_bf16_f32 v151, v162, v163
	s_cbranch_vccnz .Lv4_rare_h2
.Lv4_cont_h2:
	v_add_f32_e32 v224, v224, v188
	s_barrier
	s_setprio 0
	s_waitcnt lgkmcnt(2)
	v_mfma_f32_32x32x16_bf16 v[4:19], v[152:155], v[184:187], v[4:19]
	ds_read_b64_tr_b16 v[156:157], v3 offset:50176
	ds_read_b64_tr_b16 v[158:159], v3 offset:54272
	s_waitcnt lgkmcnt(2)
	v_mfma_f32_32x32x16_bf16 v[116:131], v[152:155], v[180:183], v[116:131]
	ds_read_b64_tr_b16 v[160:161], v3 offset:50688
	ds_read_b64_tr_b16 v[162:163], v3 offset:54784
	s_waitcnt lgkmcnt(2)
	v_mfma_f32_32x32x16_bf16 v[100:115], v[152:155], v[156:159], v[100:115]
	ds_read_b64_tr_b16 v[156:157], v3 offset:51200
	ds_read_b64_tr_b16 v[158:159], v3 offset:55296
	s_waitcnt lgkmcnt(2)
	v_mfma_f32_32x32x16_bf16 v[84:99], v[152:155], v[160:163], v[84:99]
	ds_read_b64_tr_b16 v[160:161], v3 offset:51712
	ds_read_b64_tr_b16 v[162:163], v3 offset:55808
	s_waitcnt lgkmcnt(2)
	v_mfma_f32_32x32x16_bf16 v[68:83], v[152:155], v[156:159], v[68:83]
	ds_read_b64_tr_b16 v[156:157], v3 offset:52224
	ds_read_b64_tr_b16 v[158:159], v3 offset:56320
	s_waitcnt lgkmcnt(2)
	v_mfma_f32_32x32x16_bf16 v[52:67], v[152:155], v[160:163], v[52:67]
	ds_read_b64_tr_b16 v[160:161], v3 offset:52736
	ds_read_b64_tr_b16 v[162:163], v3 offset:56832
	s_waitcnt lgkmcnt(2)
	v_mfma_f32_32x32x16_bf16 v[36:51], v[152:155], v[156:159], v[36:51]
	ds_read_b64_tr_b16 v[156:157], v3 offset:57344
	ds_read_b64_tr_b16 v[158:159], v3 offset:61440
	s_waitcnt lgkmcnt(2)
	v_mfma_f32_32x32x16_bf16 v[20:35], v[152:155], v[160:163], v[20:35]
	ds_read_b64_tr_b16 v[152:153], v3 offset:57856
	ds_read_b64_tr_b16 v[154:155], v3 offset:61952
	s_waitcnt lgkmcnt(2)
	v_mfma_f32_32x32x16_bf16 v[4:19], v[148:151], v[156:159], v[4:19]
	ds_read_b64_tr_b16 v[156:157], v3 offset:58368
	ds_read_b64_tr_b16 v[158:159], v3 offset:62464
	s_waitcnt lgkmcnt(2)
	v_mfma_f32_32x32x16_bf16 v[116:131], v[148:151], v[152:155], v[116:131]
	ds_read_b64_tr_b16 v[152:153], v3 offset:58880
	ds_read_b64_tr_b16 v[154:155], v3 offset:62976
	s_waitcnt lgkmcnt(2)
	v_mfma_f32_32x32x16_bf16 v[100:115], v[148:151], v[156:159], v[100:115]
	ds_read_b64_tr_b16 v[156:157], v3 offset:59392
	ds_read_b64_tr_b16 v[158:159], v3 offset:63488
	s_waitcnt lgkmcnt(2)
	v_mfma_f32_32x32x16_bf16 v[84:99], v[148:151], v[152:155], v[84:99]
	ds_read_b64_tr_b16 v[152:153], v3 offset:59904
	ds_read_b64_tr_b16 v[154:155], v3 offset:64000
	s_waitcnt lgkmcnt(2)
	v_mfma_f32_32x32x16_bf16 v[68:83], v[148:151], v[156:159], v[68:83]
	ds_read_b64_tr_b16 v[156:157], v3 offset:60416
	ds_read_b64_tr_b16 v[158:159], v3 offset:64512
	s_waitcnt lgkmcnt(2)
	v_mfma_f32_32x32x16_bf16 v[52:67], v[148:151], v[152:155], v[52:67]
	ds_read_b64_tr_b16 v[152:153], v3 offset:60928
	ds_read_b64_tr_b16 v[154:155], v3 offset:65024
	s_waitcnt lgkmcnt(2)
	v_mfma_f32_32x32x16_bf16 v[36:51], v[148:151], v[156:159], v[36:51]
	s_waitcnt lgkmcnt(0)
	v_mfma_f32_32x32x16_bf16 v[20:35], v[148:151], v[152:155], v[20:35]
	s_min_u32 s85, s79, s84
	s_lshl_b32 s4, s85, 6
	s_cmp_lt_u32 s85, 4
	s_cselect_b64 s[2:3], -1, 0
	s_add_i32 s88, s4, 0xffffff00
	s_and_b64 s[86:87], s[2:3], exec
	s_cselect_b32 s4, s4, s88
	s_cselect_b32 s88, s17, s73
	s_cselect_b32 s89, s16, s72
	s_lshl_b64 s[86:87], s[4:5], 7
	s_add_u32 s86, s89, s86
	s_addc_u32 s87, s88, s87
	s_lshl_b32 s88, s85, 1
	s_mov_b32 s89, s5
	s_lshl_b64 s[88:89], s[88:89], 2
	s_add_u32 s85, s18, s88
	s_addc_u32 s90, s19, s89
	s_add_u32 s88, s74, s88
	s_addc_u32 s89, s75, s89
	s_add_u32 s88, s88, 0xffffffe0
	s_addc_u32 s89, s89, -1
	s_and_b64 s[2:3], s[2:3], exec
	s_waitcnt vmcnt(0)
	v_mov_b32_e32 v236, v209
	s_cselect_b32 s3, s90, s89
	s_cselect_b32 s2, s85, s88
	s_waitcnt vmcnt(0) lgkmcnt(0)
	s_barrier
	s_setprio 1
	global_load_dwordx2 v[206:207], v201, s[2:3]
	ds_read_b128 v[180:183], v225 offset:16384
	ds_read_b128 v[184:187], v226 offset:16384
	s_cselect_b32 s85, s21, s77
	s_cselect_b32 s88, s20, s76
	s_lshl_b64 s[2:3], s[4:5], 9
	s_add_u32 s2, s88, s2
	s_addc_u32 s3, s85, s3
	s_waitcnt lgkmcnt(1)
	v_mfma_i32_32x32x32_i8 v[148:163], v[180:183], v[164:167], v[132:147]
	ds_read_b128 v[180:183], v227 offset:16384
	s_waitcnt lgkmcnt(1)
	v_mfma_i32_32x32x32_i8 v[148:163], v[184:187], v[168:171], v[148:163]
	ds_read_b128 v[188:191], v228 offset:16384
	s_waitcnt lgkmcnt(1)
	v_mfma_i32_32x32x32_i8 v[148:163], v[180:183], v[172:175], v[148:163]
	ds_read_b64_tr_b16 v[184:185], v222 offset:32768
	ds_read_b64_tr_b16 v[186:187], v222 offset:36864
	s_waitcnt lgkmcnt(2)
	v_mfma_i32_32x32x32_i8 v[148:163], v[188:191], v[176:179], v[148:163]
	ds_read_b64_tr_b16 v[180:181], v222 offset:33280
	ds_read_b64_tr_b16 v[182:183], v222 offset:37376
	s_nop 7
	s_mov_b32 s90, s94
	v_mul_f32_e32 v189, v221, v208
	v_fma_f32 v190, s100, v189, v255
	v_fma_f32 v148, v148, v189, -v190
	v_fma_f32 v149, v149, v189, -v190
	v_exp_f32_e32 v148, v148
	v_fma_f32 v150, v150, v189, -v190
	v_exp_f32_e32 v149, v149
	v_fma_f32 v151, v151, v189, -v190
	v_exp_f32_e32 v150, v150
	v_fma_f32 v152, v152, v189, -v190
	v_exp_f32_e32 v151, v151
	v_fma_f32 v153, v153, v189, -v190
	v_exp_f32_e32 v152, v152
	v_fma_f32 v154, v154, v189, -v190
	v_exp_f32_e32 v153, v153
	v_fma_f32 v155, v155, v189, -v190
	v_exp_f32_e32 v154, v154
	v_fma_f32 v156, v156, v189, -v190
	v_exp_f32_e32 v155, v155
	v_fma_f32 v157, v157, v189, -v190
	v_exp_f32_e32 v156, v156
	v_fma_f32 v158, v158, v189, -v190
	v_exp_f32_e32 v157, v157
	v_fma_f32 v159, v159, v189, -v190
	v_exp_f32_e32 v158, v158
	v_fma_f32 v160, v160, v189, -v190
	v_exp_f32_e32 v159, v159
	v_fma_f32 v161, v161, v189, -v190
	v_exp_f32_e32 v160, v160
	v_fma_f32 v162, v162, v189, -v190
	v_exp_f32_e32 v161, v161
	v_fma_f32 v163, v163, v189, -v190
	v_exp_f32_e32 v162, v162
	v_exp_f32_e32 v163, v163
	v_add_f32_e32 v188, v148, v149
	v_add_f32_e32 v189, v150, v151
	v_add_f32_e32 v190, v152, v153
	v_add_f32_e32 v191, v154, v155
	v_add_f32_e32 v192, v156, v157
	v_add_f32_e32 v193, v158, v159
	v_add_f32_e32 v194, v160, v161
	v_add_f32_e32 v195, v162, v163
	v_add_f32_e32 v188, v188, v189
	v_add_f32_e32 v190, v190, v191
	v_add_f32_e32 v192, v192, v193
	v_add_f32_e32 v194, v194, v195
	v_add_f32_e32 v188, v188, v190
	v_add_f32_e32 v192, v192, v194
	v_add_f32_e32 v188, v188, v192
	v_cmp_lt_f32_e32 vcc, s101, v188
	v_cvt_pk_bf16_f32 v155, v154, v155
	v_cvt_pk_bf16_f32 v154, v152, v153
	v_cvt_pk_bf16_f32 v152, v148, v149
	v_cvt_pk_bf16_f32 v153, v150, v151
	v_cvt_pk_bf16_f32 v148, v156, v157
	v_cvt_pk_bf16_f32 v149, v158, v159
	v_cvt_pk_bf16_f32 v150, v160, v161
	v_cvt_pk_bf16_f32 v151, v162, v163
	s_cbranch_vccnz .Lv4_rare_h3
.Lv4_cont_h3:
	v_add_f32_e32 v224, v224, v188
	s_barrier
	s_setprio 0
	s_waitcnt lgkmcnt(2)
	v_mfma_f32_32x32x16_bf16 v[4:19], v[152:155], v[184:187], v[4:19]
	ds_read_b64_tr_b16 v[156:157], v222 offset:33792
	ds_read_b64_tr_b16 v[158:159], v222 offset:37888
	s_waitcnt lgkmcnt(2)
	v_mfma_f32_32x32x16_bf16 v[116:131], v[152:155], v[180:183], v[116:131]
	ds_read_b64_tr_b16 v[160:161], v222 offset:34304
	ds_read_b64_tr_b16 v[162:163], v222 offset:38400
	s_add_i32 m0, s83, 0
	s_nop 0
	global_load_lds_dwordx4 v200, s[86:87]
	s_waitcnt lgkmcnt(2)
	v_mfma_f32_32x32x16_bf16 v[100:115], v[152:155], v[156:159], v[100:115]
	ds_read_b64_tr_b16 v[156:157], v222 offset:34816
	ds_read_b64_tr_b16 v[158:159], v222 offset:38912
	s_waitcnt lgkmcnt(2)
	v_mfma_f32_32x32x16_bf16 v[84:99], v[152:155], v[160:163], v[84:99]
	ds_read_b64_tr_b16 v[160:161], v222 offset:35328
	ds_read_b64_tr_b16 v[162:163], v222 offset:39424
	s_add_i32 m0, s82, 0
	s_nop 0
	global_load_lds_dwordx4 v204, s[2:3]
	s_waitcnt lgkmcnt(2)
	v_mfma_f32_32x32x16_bf16 v[68:83], v[152:155], v[156:159], v[68:83]
	ds_read_b64_tr_b16 v[156:157], v222 offset:35840
	ds_read_b64_tr_b16 v[158:159], v222 offset:39936
	s_waitcnt lgkmcnt(2)
	v_mfma_f32_32x32x16_bf16 v[52:67], v[152:155], v[160:163], v[52:67]
	ds_read_b64_tr_b16 v[160:161], v222 offset:36352
	ds_read_b64_tr_b16 v[162:163], v222 offset:40448
	s_add_u32 s2, s2, 0x80
	s_addc_u32 s3, s3, 0
	s_add_i32 m0, s82, 0x400
	s_nop 0
	global_load_lds_dwordx4 v204, s[2:3]
	s_waitcnt lgkmcnt(2)
	v_mfma_f32_32x32x16_bf16 v[36:51], v[152:155], v[156:159], v[36:51]
	ds_read_b64_tr_b16 v[156:157], v222 offset:40960
	ds_read_b64_tr_b16 v[158:159], v222 offset:45056
	s_waitcnt lgkmcnt(2)
	v_mfma_f32_32x32x16_bf16 v[20:35], v[152:155], v[160:163], v[20:35]
	ds_read_b64_tr_b16 v[152:153], v222 offset:41472
	ds_read_b64_tr_b16 v[154:155], v222 offset:45568
	s_add_u32 s2, s2, 0x80
	s_addc_u32 s3, s3, 0
	s_add_i32 m0, s82, 0x800
	s_nop 0
	global_load_lds_dwordx4 v204, s[2:3]
	s_waitcnt lgkmcnt(2)
	v_mfma_f32_32x32x16_bf16 v[4:19], v[148:151], v[156:159], v[4:19]
	ds_read_b64_tr_b16 v[156:157], v222 offset:41984
	ds_read_b64_tr_b16 v[158:159], v222 offset:46080
	s_waitcnt lgkmcnt(2)
	v_mfma_f32_32x32x16_bf16 v[116:131], v[148:151], v[152:155], v[116:131]
	ds_read_b64_tr_b16 v[152:153], v222 offset:42496
	ds_read_b64_tr_b16 v[154:155], v222 offset:46592
	s_add_u32 s2, s2, 0x80
	s_addc_u32 s3, s3, 0
	s_add_i32 m0, s82, 0xc00
	s_nop 0
	global_load_lds_dwordx4 v204, s[2:3]
	s_waitcnt lgkmcnt(2)
	v_mfma_f32_32x32x16_bf16 v[100:115], v[148:151], v[156:159], v[100:115]
	ds_read_b64_tr_b16 v[156:157], v222 offset:43008
	ds_read_b64_tr_b16 v[158:159], v222 offset:47104
	s_waitcnt lgkmcnt(2)
	v_mfma_f32_32x32x16_bf16 v[84:99], v[148:151], v[152:155], v[84:99]
	ds_read_b64_tr_b16 v[152:153], v222 offset:43520
	ds_read_b64_tr_b16 v[154:155], v222 offset:47616
	s_waitcnt lgkmcnt(2)
	v_mfma_f32_32x32x16_bf16 v[68:83], v[148:151], v[156:159], v[68:83]
	ds_read_b64_tr_b16 v[156:157], v222 offset:44032
	ds_read_b64_tr_b16 v[158:159], v222 offset:48128
	s_waitcnt lgkmcnt(2)
	v_mfma_f32_32x32x16_bf16 v[52:67], v[148:151], v[152:155], v[52:67]
	ds_read_b64_tr_b16 v[152:153], v222 offset:44544
	ds_read_b64_tr_b16 v[154:155], v222 offset:48640
	s_waitcnt lgkmcnt(2)
	v_mfma_f32_32x32x16_bf16 v[36:51], v[148:151], v[156:159], v[36:51]
	s_waitcnt lgkmcnt(0)
	v_mfma_f32_32x32x16_bf16 v[20:35], v[148:151], v[152:155], v[20:35]
	s_barrier
	s_setprio 1
	ds_read_b128 v[180:183], v225 offset:20480
	ds_read_b128 v[184:187], v226 offset:20480
	s_waitcnt lgkmcnt(1)
	v_mfma_i32_32x32x32_i8 v[148:163], v[180:183], v[164:167], v[132:147]
	ds_read_b128 v[180:183], v227 offset:20480
	s_waitcnt lgkmcnt(1)
	v_mfma_i32_32x32x32_i8 v[148:163], v[184:187], v[168:171], v[148:163]
	ds_read_b128 v[188:191], v228 offset:20480
	s_waitcnt lgkmcnt(1)
	v_mfma_i32_32x32x32_i8 v[148:163], v[180:183], v[172:175], v[148:163]
	ds_read_b64_tr_b16 v[184:185], v222 offset:49152
	ds_read_b64_tr_b16 v[186:187], v222 offset:53248
	s_waitcnt lgkmcnt(2)
	v_mfma_i32_32x32x32_i8 v[148:163], v[188:191], v[176:179], v[148:163]
	ds_read_b64_tr_b16 v[180:181], v222 offset:49664
	ds_read_b64_tr_b16 v[182:183], v222 offset:53760
	s_nop 7
	v_mul_f32_e32 v189, v221, v236
	v_fma_f32 v190, s100, v189, v255
	v_fma_f32 v148, v148, v189, -v190
	v_fma_f32 v149, v149, v189, -v190
	v_exp_f32_e32 v148, v148
	v_fma_f32 v150, v150, v189, -v190
	v_exp_f32_e32 v149, v149
	v_fma_f32 v151, v151, v189, -v190
	v_exp_f32_e32 v150, v150
	v_fma_f32 v152, v152, v189, -v190
	v_exp_f32_e32 v151, v151
	v_fma_f32 v153, v153, v189, -v190
	v_exp_f32_e32 v152, v152
	v_fma_f32 v154, v154, v189, -v190
	v_exp_f32_e32 v153, v153
	v_fma_f32 v155, v155, v189, -v190
	v_exp_f32_e32 v154, v154
	v_fma_f32 v156, v156, v189, -v190
	v_exp_f32_e32 v155, v155
	v_fma_f32 v157, v157, v189, -v190
	v_exp_f32_e32 v156, v156
	v_fma_f32 v158, v158, v189, -v190
	v_exp_f32_e32 v157, v157
	v_fma_f32 v159, v159, v189, -v190
	v_exp_f32_e32 v158, v158
	v_fma_f32 v160, v160, v189, -v190
	v_exp_f32_e32 v159, v159
	v_fma_f32 v161, v161, v189, -v190
	v_exp_f32_e32 v160, v160
	v_fma_f32 v162, v162, v189, -v190
	v_exp_f32_e32 v161, v161
	v_fma_f32 v163, v163, v189, -v190
	v_exp_f32_e32 v162, v162
	v_exp_f32_e32 v163, v163
	v_add_f32_e32 v188, v148, v149
	v_add_f32_e32 v189, v150, v151
	v_add_f32_e32 v190, v152, v153
	v_add_f32_e32 v191, v154, v155
	v_add_f32_e32 v192, v156, v157
	v_add_f32_e32 v193, v158, v159
	v_add_f32_e32 v194, v160, v161
	v_add_f32_e32 v195, v162, v163
	v_add_f32_e32 v188, v188, v189
	v_add_f32_e32 v190, v190, v191
	v_add_f32_e32 v192, v192, v193
	v_add_f32_e32 v194, v194, v195
	v_add_f32_e32 v188, v188, v190
	v_add_f32_e32 v192, v192, v194
	v_add_f32_e32 v188, v188, v192
	v_cmp_lt_f32_e32 vcc, s101, v188
	v_cvt_pk_bf16_f32 v155, v154, v155
	v_cvt_pk_bf16_f32 v154, v152, v153
	v_cvt_pk_bf16_f32 v152, v148, v149
	v_cvt_pk_bf16_f32 v153, v150, v151
	v_cvt_pk_bf16_f32 v148, v156, v157
	v_cvt_pk_bf16_f32 v149, v158, v159
	v_cvt_pk_bf16_f32 v150, v160, v161
	v_cvt_pk_bf16_f32 v151, v162, v163
	s_cbranch_vccnz .Lv4_rare_h4
; __device__ __forceinline__ void attn_unit256q(const bf16* __restrict__ Qb, const unsigned char* __restrict__ Kc, const unsigned char* __restrict__ Kl, const float* __restrict__ Sc, const float* __restrict__ Sl, ...
;     ...
;   for (int j = 0; j < NT; j += 2) {
;     A5_TILE(0, 0, KBUF, VBUF, j);
;     A5_TILE(KBUF, VBUF, 0, 0, j + 1);
;   }
.Lv4_cont_h4:
	v_add_f32_e32 v224, v224, v188
	s_barrier
	s_setprio 0
	s_waitcnt lgkmcnt(2)
	v_mfma_f32_32x32x16_bf16 v[4:19], v[152:155], v[184:187], v[4:19]
	ds_read_b64_tr_b16 v[156:157], v222 offset:50176
	ds_read_b64_tr_b16 v[158:159], v222 offset:54272
	s_waitcnt lgkmcnt(2)
	v_mfma_f32_32x32x16_bf16 v[116:131], v[152:155], v[180:183], v[116:131]
	ds_read_b64_tr_b16 v[160:161], v222 offset:50688
	ds_read_b64_tr_b16 v[162:163], v222 offset:54784
	s_waitcnt lgkmcnt(2)
	v_mfma_f32_32x32x16_bf16 v[100:115], v[152:155], v[156:159], v[100:115]
	ds_read_b64_tr_b16 v[156:157], v222 offset:51200
	ds_read_b64_tr_b16 v[158:159], v222 offset:55296
	s_waitcnt lgkmcnt(2)
	v_mfma_f32_32x32x16_bf16 v[84:99], v[152:155], v[160:163], v[84:99]
	ds_read_b64_tr_b16 v[160:161], v222 offset:51712
	ds_read_b64_tr_b16 v[162:163], v222 offset:55808
	s_waitcnt lgkmcnt(2)
	v_mfma_f32_32x32x16_bf16 v[68:83], v[152:155], v[156:159], v[68:83]
	ds_read_b64_tr_b16 v[156:157], v222 offset:52224
	ds_read_b64_tr_b16 v[158:159], v222 offset:56320
	s_waitcnt lgkmcnt(2)
	v_mfma_f32_32x32x16_bf16 v[52:67], v[152:155], v[160:163], v[52:67]
	ds_read_b64_tr_b16 v[160:161], v222 offset:52736
	ds_read_b64_tr_b16 v[162:163], v222 offset:56832
	s_waitcnt lgkmcnt(2)
	v_mfma_f32_32x32x16_bf16 v[36:51], v[152:155], v[156:159], v[36:51]
	ds_read_b64_tr_b16 v[156:157], v222 offset:57344
	ds_read_b64_tr_b16 v[158:159], v222 offset:61440
	s_waitcnt lgkmcnt(2)
	v_mfma_f32_32x32x16_bf16 v[20:35], v[152:155], v[160:163], v[20:35]
	ds_read_b64_tr_b16 v[152:153], v222 offset:57856
	ds_read_b64_tr_b16 v[154:155], v222 offset:61952
	s_waitcnt lgkmcnt(2)
	v_mfma_f32_32x32x16_bf16 v[4:19], v[148:151], v[156:159], v[4:19]
	ds_read_b64_tr_b16 v[156:157], v222 offset:58368
	ds_read_b64_tr_b16 v[158:159], v222 offset:62464
	s_waitcnt lgkmcnt(2)
	v_mfma_f32_32x32x16_bf16 v[116:131], v[148:151], v[152:155], v[116:131]
	ds_read_b64_tr_b16 v[152:153], v222 offset:58880
	ds_read_b64_tr_b16 v[154:155], v222 offset:62976
	s_waitcnt lgkmcnt(2)
	v_mfma_f32_32x32x16_bf16 v[100:115], v[148:151], v[156:159], v[100:115]
	ds_read_b64_tr_b16 v[156:157], v222 offset:59392
	ds_read_b64_tr_b16 v[158:159], v222 offset:63488
	s_waitcnt lgkmcnt(2)
	v_mfma_f32_32x32x16_bf16 v[84:99], v[148:151], v[152:155], v[84:99]
	ds_read_b64_tr_b16 v[152:153], v222 offset:59904
	ds_read_b64_tr_b16 v[154:155], v222 offset:64000
	s_waitcnt lgkmcnt(2)
	v_mfma_f32_32x32x16_bf16 v[68:83], v[148:151], v[156:159], v[68:83]
	ds_read_b64_tr_b16 v[156:157], v222 offset:60416
	ds_read_b64_tr_b16 v[158:159], v222 offset:64512
	s_waitcnt lgkmcnt(2)
	v_mfma_f32_32x32x16_bf16 v[52:67], v[148:151], v[152:155], v[52:67]
	ds_read_b64_tr_b16 v[152:153], v222 offset:60928
	ds_read_b64_tr_b16 v[154:155], v222 offset:65024
	s_waitcnt lgkmcnt(2)
	v_mfma_f32_32x32x16_bf16 v[36:51], v[148:151], v[156:159], v[36:51]
	s_waitcnt lgkmcnt(0)
	v_mfma_f32_32x32x16_bf16 v[20:35], v[148:151], v[152:155], v[20:35]
	s_add_i32 s2, s79, 2
	s_cmp_ge_u32 s79, s70
	s_cbranch_scc1 .LBB0_557
	s_mov_b32 s79, s2
	s_branch .LBB0_538
.Lv4_rare_h1:
	ds_read_b128 v[244:247], v225
	ds_read_b128 v[248:251], v226
	s_waitcnt lgkmcnt(1)
	v_mfma_i32_32x32x32_i8 v[148:163], v[244:247], v[164:167], v[132:147]
	ds_read_b128 v[244:247], v227
	s_waitcnt lgkmcnt(1)
	v_mfma_i32_32x32x32_i8 v[148:163], v[248:251], v[168:171], v[148:163]
	ds_read_b128 v[248:251], v228
	s_waitcnt lgkmcnt(1)
	v_mfma_i32_32x32x32_i8 v[148:163], v[244:247], v[172:175], v[148:163]
	s_waitcnt lgkmcnt(0)
	v_mfma_i32_32x32x32_i8 v[148:163], v[248:251], v[176:179], v[148:163]
	s_nop 15
	v_max3_f32 v188, v148, v149, v150
	v_max3_f32 v189, v151, v152, v153
	v_max3_f32 v190, v154, v155, v156
	v_max3_f32 v191, v157, v158, v159
	v_max3_f32 v192, v160, v161, v162
	v_max3_f32 v188, v188, v189, v190
	v_max3_f32 v191, v191, v192, v163
	v_max_f32_e32 v188, v188, v191
	v_add_f32_e32 v188, 0xcb400000, v188
	v_mov_b32_e32 v189, v188
	s_nop 1
	v_permlane32_swap_b32_e32 v188, v189
	v_max_f32_e32 v188, v188, v189
	v_mul_f32_e32 v189, v206, v188
	v_fma_f32 v188, v206, v188, -v237
	v_max_f32_e32 v189, v237, v189
	v_cmp_gt_f32_e32 vcc, v188, v220
	s_nop 1
	v_cndmask_b32_e32 v189, v237, v189, vcc
	v_sub_f32_e32 v188, v237, v189
	v_mul_f32_e32 v188, v221, v188
	v_exp_f32_e32 v254, v188
	v_mov_b32_e32 v237, v189
	v_mul_f32_e32 v255, v221, v189
	v_mul_f32_e32 v224, v224, v254
	s_and_saveexec_b64 vcc, s[0:1]
	ds_write_b32 v223, v254
	s_or_b64 exec, exec, vcc
	s_waitcnt lgkmcnt(0)
	v_add_u32_e32 v253, s78, v218
	ds_read_b128 v[244:247], v253 offset:96
	ds_read_b128 v[248:251], v253 offset:64
	s_waitcnt lgkmcnt(1)
	v_pk_mul_f32 v[16:17], v[16:17], v[244:245]
	v_pk_mul_f32 v[18:19], v[18:19], v[246:247]
	v_pk_mul_f32 v[128:129], v[128:129], v[244:245]
	v_pk_mul_f32 v[130:131], v[130:131], v[246:247]
	v_pk_mul_f32 v[112:113], v[112:113], v[244:245]
	v_pk_mul_f32 v[114:115], v[114:115], v[246:247]
	v_pk_mul_f32 v[96:97], v[96:97], v[244:245]
	v_pk_mul_f32 v[98:99], v[98:99], v[246:247]
	v_pk_mul_f32 v[80:81], v[80:81], v[244:245]
	v_pk_mul_f32 v[82:83], v[82:83], v[246:247]
	v_pk_mul_f32 v[64:65], v[64:65], v[244:245]
	v_pk_mul_f32 v[66:67], v[66:67], v[246:247]
	v_pk_mul_f32 v[48:49], v[48:49], v[244:245]
	v_pk_mul_f32 v[50:51], v[50:51], v[246:247]
	v_pk_mul_f32 v[32:33], v[32:33], v[244:245]
	v_pk_mul_f32 v[34:35], v[34:35], v[246:247]
	s_waitcnt lgkmcnt(0)
	v_pk_mul_f32 v[12:13], v[12:13], v[248:249]
	v_pk_mul_f32 v[14:15], v[14:15], v[250:251]
	v_pk_mul_f32 v[124:125], v[124:125], v[248:249]
	v_pk_mul_f32 v[126:127], v[126:127], v[250:251]
	v_pk_mul_f32 v[108:109], v[108:109], v[248:249]
	v_pk_mul_f32 v[110:111], v[110:111], v[250:251]
	v_pk_mul_f32 v[92:93], v[92:93], v[248:249]
	v_pk_mul_f32 v[94:95], v[94:95], v[250:251]
	v_pk_mul_f32 v[76:77], v[76:77], v[248:249]
	v_pk_mul_f32 v[78:79], v[78:79], v[250:251]
	v_pk_mul_f32 v[60:61], v[60:61], v[248:249]
	v_pk_mul_f32 v[62:63], v[62:63], v[250:251]
	v_pk_mul_f32 v[44:45], v[44:45], v[248:249]
	v_pk_mul_f32 v[46:47], v[46:47], v[250:251]
	v_pk_mul_f32 v[28:29], v[28:29], v[248:249]
	v_pk_mul_f32 v[30:31], v[30:31], v[250:251]
	ds_read_b128 v[244:247], v253 offset:32
	ds_read_b128 v[248:251], v253
	s_waitcnt lgkmcnt(1)
	v_pk_mul_f32 v[8:9], v[8:9], v[244:245]
	v_pk_mul_f32 v[10:11], v[10:11], v[246:247]
	v_pk_mul_f32 v[120:121], v[120:121], v[244:245]
	v_pk_mul_f32 v[122:123], v[122:123], v[246:247]
	v_pk_mul_f32 v[104:105], v[104:105], v[244:245]
	v_pk_mul_f32 v[106:107], v[106:107], v[246:247]
	v_pk_mul_f32 v[88:89], v[88:89], v[244:245]
	v_pk_mul_f32 v[90:91], v[90:91], v[246:247]
	v_pk_mul_f32 v[72:73], v[72:73], v[244:245]
	v_pk_mul_f32 v[74:75], v[74:75], v[246:247]
	v_pk_mul_f32 v[56:57], v[56:57], v[244:245]
	v_pk_mul_f32 v[58:59], v[58:59], v[246:247]
	v_pk_mul_f32 v[40:41], v[40:41], v[244:245]
	v_pk_mul_f32 v[42:43], v[42:43], v[246:247]
	v_pk_mul_f32 v[24:25], v[24:25], v[244:245]
	v_pk_mul_f32 v[26:27], v[26:27], v[246:247]
	s_waitcnt lgkmcnt(0)
	v_pk_mul_f32 v[4:5], v[4:5], v[248:249]
	v_pk_mul_f32 v[6:7], v[6:7], v[250:251]
	v_pk_mul_f32 v[116:117], v[116:117], v[248:249]
	v_pk_mul_f32 v[118:119], v[118:119], v[250:251]
	v_pk_mul_f32 v[100:101], v[100:101], v[248:249]
	v_pk_mul_f32 v[102:103], v[102:103], v[250:251]
	v_pk_mul_f32 v[84:85], v[84:85], v[248:249]
	v_pk_mul_f32 v[86:87], v[86:87], v[250:251]
	v_pk_mul_f32 v[68:69], v[68:69], v[248:249]
	v_pk_mul_f32 v[70:71], v[70:71], v[250:251]
	v_pk_mul_f32 v[52:53], v[52:53], v[248:249]
	v_pk_mul_f32 v[54:55], v[54:55], v[250:251]
	v_pk_mul_f32 v[36:37], v[36:37], v[248:249]
	v_pk_mul_f32 v[38:39], v[38:39], v[250:251]
	v_pk_mul_f32 v[20:21], v[20:21], v[248:249]
	v_pk_mul_f32 v[22:23], v[22:23], v[250:251]
	v_mul_f32_e32 v189, v221, v206
	v_fma_f32 v190, s100, v189, v255
	v_fma_f32 v148, v148, v189, -v190
	v_fma_f32 v149, v149, v189, -v190
	v_exp_f32_e32 v148, v148
	v_fma_f32 v150, v150, v189, -v190
	v_exp_f32_e32 v149, v149
	v_fma_f32 v151, v151, v189, -v190
	v_exp_f32_e32 v150, v150
	v_fma_f32 v152, v152, v189, -v190
	v_exp_f32_e32 v151, v151
	v_fma_f32 v153, v153, v189, -v190
	v_exp_f32_e32 v152, v152
	v_fma_f32 v154, v154, v189, -v190
	v_exp_f32_e32 v153, v153
	v_fma_f32 v155, v155, v189, -v190
	v_exp_f32_e32 v154, v154
	v_fma_f32 v156, v156, v189, -v190
	v_exp_f32_e32 v155, v155
	v_fma_f32 v157, v157, v189, -v190
	v_exp_f32_e32 v156, v156
	v_fma_f32 v158, v158, v189, -v190
	v_exp_f32_e32 v157, v157
	v_fma_f32 v159, v159, v189, -v190
	v_exp_f32_e32 v158, v158
	v_fma_f32 v160, v160, v189, -v190
	v_exp_f32_e32 v159, v159
	v_fma_f32 v161, v161, v189, -v190
	v_exp_f32_e32 v160, v160
	v_fma_f32 v162, v162, v189, -v190
	v_exp_f32_e32 v161, v161
	v_fma_f32 v163, v163, v189, -v190
	v_exp_f32_e32 v162, v162
	v_exp_f32_e32 v163, v163
	v_add_f32_e32 v188, v148, v149
	v_add_f32_e32 v189, v150, v151
	v_add_f32_e32 v190, v152, v153
	v_add_f32_e32 v191, v154, v155
	v_add_f32_e32 v192, v156, v157
	v_add_f32_e32 v193, v158, v159
	v_add_f32_e32 v194, v160, v161
	v_add_f32_e32 v195, v162, v163
	v_add_f32_e32 v188, v188, v189
	v_add_f32_e32 v190, v190, v191
	v_add_f32_e32 v192, v192, v193
	v_add_f32_e32 v194, v194, v195
	v_add_f32_e32 v188, v188, v190
	v_add_f32_e32 v192, v192, v194
	v_add_f32_e32 v188, v188, v192
	v_cvt_pk_bf16_f32 v155, v154, v155
	v_cvt_pk_bf16_f32 v154, v152, v153
	v_cvt_pk_bf16_f32 v152, v148, v149
	v_cvt_pk_bf16_f32 v153, v150, v151
	v_cvt_pk_bf16_f32 v148, v156, v157
	v_cvt_pk_bf16_f32 v149, v158, v159
	v_cvt_pk_bf16_f32 v150, v160, v161
	v_cvt_pk_bf16_f32 v151, v162, v163
	s_branch .Lv4_cont_h1
.Lv4_rare_h2:
	ds_read_b128 v[244:247], v225 offset:4096
	ds_read_b128 v[248:251], v226 offset:4096
	s_waitcnt lgkmcnt(1)
	v_mfma_i32_32x32x32_i8 v[148:163], v[244:247], v[164:167], v[132:147]
	ds_read_b128 v[244:247], v227 offset:4096
	s_waitcnt lgkmcnt(1)
	v_mfma_i32_32x32x32_i8 v[148:163], v[248:251], v[168:171], v[148:163]
	ds_read_b128 v[248:251], v228 offset:4096
	s_waitcnt lgkmcnt(1)
	v_mfma_i32_32x32x32_i8 v[148:163], v[244:247], v[172:175], v[148:163]
	s_waitcnt lgkmcnt(0)
	v_mfma_i32_32x32x32_i8 v[148:163], v[248:251], v[176:179], v[148:163]
	s_nop 15
	v_max3_f32 v188, v148, v149, v150
	v_max3_f32 v189, v151, v152, v153
	v_max3_f32 v190, v154, v155, v156
	v_max3_f32 v191, v157, v158, v159
	v_max3_f32 v192, v160, v161, v162
	v_max3_f32 v188, v188, v189, v190
	v_max3_f32 v191, v191, v192, v163
	v_max_f32_e32 v188, v188, v191
	v_add_f32_e32 v188, 0xcb400000, v188
	v_mov_b32_e32 v189, v188
	s_nop 1
	v_permlane32_swap_b32_e32 v188, v189
	v_max_f32_e32 v188, v188, v189
	v_mul_f32_e32 v189, v207, v188
	v_fma_f32 v188, v207, v188, -v237
	v_max_f32_e32 v189, v237, v189
	v_cmp_gt_f32_e32 vcc, v188, v220
	s_nop 1
	v_cndmask_b32_e32 v189, v237, v189, vcc
	v_sub_f32_e32 v188, v237, v189
	v_mul_f32_e32 v188, v221, v188
	v_exp_f32_e32 v254, v188
	v_mov_b32_e32 v237, v189
	v_mul_f32_e32 v255, v221, v189
	v_mul_f32_e32 v224, v224, v254
	s_and_saveexec_b64 vcc, s[0:1]
	ds_write_b32 v223, v254
	s_or_b64 exec, exec, vcc
	s_waitcnt lgkmcnt(0)
	v_add_u32_e32 v253, s78, v218
	ds_read_b128 v[244:247], v253 offset:96
	ds_read_b128 v[248:251], v253 offset:64
	s_waitcnt lgkmcnt(1)
	v_pk_mul_f32 v[16:17], v[16:17], v[244:245]
	v_pk_mul_f32 v[18:19], v[18:19], v[246:247]
	v_pk_mul_f32 v[128:129], v[128:129], v[244:245]
	v_pk_mul_f32 v[130:131], v[130:131], v[246:247]
	v_pk_mul_f32 v[112:113], v[112:113], v[244:245]
	v_pk_mul_f32 v[114:115], v[114:115], v[246:247]
	v_pk_mul_f32 v[96:97], v[96:97], v[244:245]
	v_pk_mul_f32 v[98:99], v[98:99], v[246:247]
	v_pk_mul_f32 v[80:81], v[80:81], v[244:245]
	v_pk_mul_f32 v[82:83], v[82:83], v[246:247]
	v_pk_mul_f32 v[64:65], v[64:65], v[244:245]
	v_pk_mul_f32 v[66:67], v[66:67], v[246:247]
	v_pk_mul_f32 v[48:49], v[48:49], v[244:245]
	v_pk_mul_f32 v[50:51], v[50:51], v[246:247]
	v_pk_mul_f32 v[32:33], v[32:33], v[244:245]
	v_pk_mul_f32 v[34:35], v[34:35], v[246:247]
	s_waitcnt lgkmcnt(0)
	v_pk_mul_f32 v[12:13], v[12:13], v[248:249]
	v_pk_mul_f32 v[14:15], v[14:15], v[250:251]
	v_pk_mul_f32 v[124:125], v[124:125], v[248:249]
	v_pk_mul_f32 v[126:127], v[126:127], v[250:251]
	v_pk_mul_f32 v[108:109], v[108:109], v[248:249]
	v_pk_mul_f32 v[110:111], v[110:111], v[250:251]
	v_pk_mul_f32 v[92:93], v[92:93], v[248:249]
	v_pk_mul_f32 v[94:95], v[94:95], v[250:251]
	v_pk_mul_f32 v[76:77], v[76:77], v[248:249]
	v_pk_mul_f32 v[78:79], v[78:79], v[250:251]
	v_pk_mul_f32 v[60:61], v[60:61], v[248:249]
	v_pk_mul_f32 v[62:63], v[62:63], v[250:251]
	v_pk_mul_f32 v[44:45], v[44:45], v[248:249]
	v_pk_mul_f32 v[46:47], v[46:47], v[250:251]
	v_pk_mul_f32 v[28:29], v[28:29], v[248:249]
	v_pk_mul_f32 v[30:31], v[30:31], v[250:251]
	ds_read_b128 v[244:247], v253 offset:32
	ds_read_b128 v[248:251], v253
	s_waitcnt lgkmcnt(1)
	v_pk_mul_f32 v[8:9], v[8:9], v[244:245]
	v_pk_mul_f32 v[10:11], v[10:11], v[246:247]
	v_pk_mul_f32 v[120:121], v[120:121], v[244:245]
	v_pk_mul_f32 v[122:123], v[122:123], v[246:247]
	v_pk_mul_f32 v[104:105], v[104:105], v[244:245]
	v_pk_mul_f32 v[106:107], v[106:107], v[246:247]
	v_pk_mul_f32 v[88:89], v[88:89], v[244:245]
	v_pk_mul_f32 v[90:91], v[90:91], v[246:247]
	v_pk_mul_f32 v[72:73], v[72:73], v[244:245]
	v_pk_mul_f32 v[74:75], v[74:75], v[246:247]
	v_pk_mul_f32 v[56:57], v[56:57], v[244:245]
	v_pk_mul_f32 v[58:59], v[58:59], v[246:247]
	v_pk_mul_f32 v[40:41], v[40:41], v[244:245]
	v_pk_mul_f32 v[42:43], v[42:43], v[246:247]
	v_pk_mul_f32 v[24:25], v[24:25], v[244:245]
	v_pk_mul_f32 v[26:27], v[26:27], v[246:247]
	s_waitcnt lgkmcnt(0)
	v_pk_mul_f32 v[4:5], v[4:5], v[248:249]
	v_pk_mul_f32 v[6:7], v[6:7], v[250:251]
	v_pk_mul_f32 v[116:117], v[116:117], v[248:249]
	v_pk_mul_f32 v[118:119], v[118:119], v[250:251]
	v_pk_mul_f32 v[100:101], v[100:101], v[248:249]
	v_pk_mul_f32 v[102:103], v[102:103], v[250:251]
	v_pk_mul_f32 v[84:85], v[84:85], v[248:249]
	v_pk_mul_f32 v[86:87], v[86:87], v[250:251]
	v_pk_mul_f32 v[68:69], v[68:69], v[248:249]
	v_pk_mul_f32 v[70:71], v[70:71], v[250:251]
	v_pk_mul_f32 v[52:53], v[52:53], v[248:249]
	v_pk_mul_f32 v[54:55], v[54:55], v[250:251]
	v_pk_mul_f32 v[36:37], v[36:37], v[248:249]
	v_pk_mul_f32 v[38:39], v[38:39], v[250:251]
	v_pk_mul_f32 v[20:21], v[20:21], v[248:249]
	v_pk_mul_f32 v[22:23], v[22:23], v[250:251]
	v_mul_f32_e32 v189, v221, v207
	v_fma_f32 v190, s100, v189, v255
	v_fma_f32 v148, v148, v189, -v190
	v_fma_f32 v149, v149, v189, -v190
	v_exp_f32_e32 v148, v148
	v_fma_f32 v150, v150, v189, -v190
	v_exp_f32_e32 v149, v149
	v_fma_f32 v151, v151, v189, -v190
	v_exp_f32_e32 v150, v150
	v_fma_f32 v152, v152, v189, -v190
	v_exp_f32_e32 v151, v151
	v_fma_f32 v153, v153, v189, -v190
	v_exp_f32_e32 v152, v152
	v_fma_f32 v154, v154, v189, -v190
	v_exp_f32_e32 v153, v153
	v_fma_f32 v155, v155, v189, -v190
	v_exp_f32_e32 v154, v154
	v_fma_f32 v156, v156, v189, -v190
	v_exp_f32_e32 v155, v155
	v_fma_f32 v157, v157, v189, -v190
	v_exp_f32_e32 v156, v156
	v_fma_f32 v158, v158, v189, -v190
	v_exp_f32_e32 v157, v157
	v_fma_f32 v159, v159, v189, -v190
	v_exp_f32_e32 v158, v158
	v_fma_f32 v160, v160, v189, -v190
	v_exp_f32_e32 v159, v159
	v_fma_f32 v161, v161, v189, -v190
	v_exp_f32_e32 v160, v160
	v_fma_f32 v162, v162, v189, -v190
	v_exp_f32_e32 v161, v161
	v_fma_f32 v163, v163, v189, -v190
	v_exp_f32_e32 v162, v162
	v_exp_f32_e32 v163, v163
	v_add_f32_e32 v188, v148, v149
	v_add_f32_e32 v189, v150, v151
	v_add_f32_e32 v190, v152, v153
	v_add_f32_e32 v191, v154, v155
	v_add_f32_e32 v192, v156, v157
	v_add_f32_e32 v193, v158, v159
	v_add_f32_e32 v194, v160, v161
	v_add_f32_e32 v195, v162, v163
	v_add_f32_e32 v188, v188, v189
	v_add_f32_e32 v190, v190, v191
	v_add_f32_e32 v192, v192, v193
	v_add_f32_e32 v194, v194, v195
	v_add_f32_e32 v188, v188, v190
	v_add_f32_e32 v192, v192, v194
	v_add_f32_e32 v188, v188, v192
	v_cvt_pk_bf16_f32 v155, v154, v155
	v_cvt_pk_bf16_f32 v154, v152, v153
	v_cvt_pk_bf16_f32 v152, v148, v149
	v_cvt_pk_bf16_f32 v153, v150, v151
	v_cvt_pk_bf16_f32 v148, v156, v157
	v_cvt_pk_bf16_f32 v149, v158, v159
	v_cvt_pk_bf16_f32 v150, v160, v161
	v_cvt_pk_bf16_f32 v151, v162, v163
	s_branch .Lv4_cont_h2
.Lv4_rare_h3:
	ds_read_b128 v[244:247], v225 offset:16384
	ds_read_b128 v[248:251], v226 offset:16384
	s_waitcnt lgkmcnt(1)
	v_mfma_i32_32x32x32_i8 v[148:163], v[244:247], v[164:167], v[132:147]
	ds_read_b128 v[244:247], v227 offset:16384
	s_waitcnt lgkmcnt(1)
	v_mfma_i32_32x32x32_i8 v[148:163], v[248:251], v[168:171], v[148:163]
	ds_read_b128 v[248:251], v228 offset:16384
	s_waitcnt lgkmcnt(1)
	v_mfma_i32_32x32x32_i8 v[148:163], v[244:247], v[172:175], v[148:163]
	s_waitcnt lgkmcnt(0)
	v_mfma_i32_32x32x32_i8 v[148:163], v[248:251], v[176:179], v[148:163]
	s_nop 15
	v_max3_f32 v188, v148, v149, v150
	v_max3_f32 v189, v151, v152, v153
	v_max3_f32 v190, v154, v155, v156
	v_max3_f32 v191, v157, v158, v159
	v_max3_f32 v192, v160, v161, v162
	v_max3_f32 v188, v188, v189, v190
	v_max3_f32 v191, v191, v192, v163
	v_max_f32_e32 v188, v188, v191
	v_add_f32_e32 v188, 0xcb400000, v188
	v_mov_b32_e32 v189, v188
	s_nop 1
	v_permlane32_swap_b32_e32 v188, v189
	v_max_f32_e32 v188, v188, v189
	v_mul_f32_e32 v189, v208, v188
	v_fma_f32 v188, v208, v188, -v237
	v_max_f32_e32 v189, v237, v189
	v_cmp_gt_f32_e32 vcc, v188, v220
	s_nop 1
	v_cndmask_b32_e32 v189, v237, v189, vcc
	v_sub_f32_e32 v188, v237, v189
	v_mul_f32_e32 v188, v221, v188
	v_exp_f32_e32 v254, v188
	v_mov_b32_e32 v237, v189
	v_mul_f32_e32 v255, v221, v189
	v_mul_f32_e32 v224, v224, v254
	s_and_saveexec_b64 vcc, s[0:1]
	ds_write_b32 v223, v254
	s_or_b64 exec, exec, vcc
	s_waitcnt lgkmcnt(0)
	v_add_u32_e32 v253, s78, v218
	ds_read_b128 v[244:247], v253 offset:96
	ds_read_b128 v[248:251], v253 offset:64
	s_waitcnt lgkmcnt(1)
	v_pk_mul_f32 v[16:17], v[16:17], v[244:245]
	v_pk_mul_f32 v[18:19], v[18:19], v[246:247]
	v_pk_mul_f32 v[128:129], v[128:129], v[244:245]
	v_pk_mul_f32 v[130:131], v[130:131], v[246:247]
	v_pk_mul_f32 v[112:113], v[112:113], v[244:245]
	v_pk_mul_f32 v[114:115], v[114:115], v[246:247]
	v_pk_mul_f32 v[96:97], v[96:97], v[244:245]
	v_pk_mul_f32 v[98:99], v[98:99], v[246:247]
	v_pk_mul_f32 v[80:81], v[80:81], v[244:245]
	v_pk_mul_f32 v[82:83], v[82:83], v[246:247]
	v_pk_mul_f32 v[64:65], v[64:65], v[244:245]
	v_pk_mul_f32 v[66:67], v[66:67], v[246:247]
	v_pk_mul_f32 v[48:49], v[48:49], v[244:245]
	v_pk_mul_f32 v[50:51], v[50:51], v[246:247]
	v_pk_mul_f32 v[32:33], v[32:33], v[244:245]
	v_pk_mul_f32 v[34:35], v[34:35], v[246:247]
	s_waitcnt lgkmcnt(0)
	v_pk_mul_f32 v[12:13], v[12:13], v[248:249]
	v_pk_mul_f32 v[14:15], v[14:15], v[250:251]
	v_pk_mul_f32 v[124:125], v[124:125], v[248:249]
	v_pk_mul_f32 v[126:127], v[126:127], v[250:251]
	v_pk_mul_f32 v[108:109], v[108:109], v[248:249]
	v_pk_mul_f32 v[110:111], v[110:111], v[250:251]
	v_pk_mul_f32 v[92:93], v[92:93], v[248:249]
	v_pk_mul_f32 v[94:95], v[94:95], v[250:251]
	v_pk_mul_f32 v[76:77], v[76:77], v[248:249]
	v_pk_mul_f32 v[78:79], v[78:79], v[250:251]
	v_pk_mul_f32 v[60:61], v[60:61], v[248:249]
	v_pk_mul_f32 v[62:63], v[62:63], v[250:251]
	v_pk_mul_f32 v[44:45], v[44:45], v[248:249]
	v_pk_mul_f32 v[46:47], v[46:47], v[250:251]
	v_pk_mul_f32 v[28:29], v[28:29], v[248:249]
	v_pk_mul_f32 v[30:31], v[30:31], v[250:251]
	ds_read_b128 v[244:247], v253 offset:32
	ds_read_b128 v[248:251], v253
	s_waitcnt lgkmcnt(1)
	v_pk_mul_f32 v[8:9], v[8:9], v[244:245]
	v_pk_mul_f32 v[10:11], v[10:11], v[246:247]
	v_pk_mul_f32 v[120:121], v[120:121], v[244:245]
	v_pk_mul_f32 v[122:123], v[122:123], v[246:247]
	v_pk_mul_f32 v[104:105], v[104:105], v[244:245]
	v_pk_mul_f32 v[106:107], v[106:107], v[246:247]
	v_pk_mul_f32 v[88:89], v[88:89], v[244:245]
	v_pk_mul_f32 v[90:91], v[90:91], v[246:247]
	v_pk_mul_f32 v[72:73], v[72:73], v[244:245]
	v_pk_mul_f32 v[74:75], v[74:75], v[246:247]
	v_pk_mul_f32 v[56:57], v[56:57], v[244:245]
	v_pk_mul_f32 v[58:59], v[58:59], v[246:247]
	v_pk_mul_f32 v[40:41], v[40:41], v[244:245]
	v_pk_mul_f32 v[42:43], v[42:43], v[246:247]
	v_pk_mul_f32 v[24:25], v[24:25], v[244:245]
	v_pk_mul_f32 v[26:27], v[26:27], v[246:247]
	s_waitcnt lgkmcnt(0)
	v_pk_mul_f32 v[4:5], v[4:5], v[248:249]
	v_pk_mul_f32 v[6:7], v[6:7], v[250:251]
	v_pk_mul_f32 v[116:117], v[116:117], v[248:249]
	v_pk_mul_f32 v[118:119], v[118:119], v[250:251]
	v_pk_mul_f32 v[100:101], v[100:101], v[248:249]
	v_pk_mul_f32 v[102:103], v[102:103], v[250:251]
	v_pk_mul_f32 v[84:85], v[84:85], v[248:249]
	v_pk_mul_f32 v[86:87], v[86:87], v[250:251]
	v_pk_mul_f32 v[68:69], v[68:69], v[248:249]
	v_pk_mul_f32 v[70:71], v[70:71], v[250:251]
	v_pk_mul_f32 v[52:53], v[52:53], v[248:249]
	v_pk_mul_f32 v[54:55], v[54:55], v[250:251]
	v_pk_mul_f32 v[36:37], v[36:37], v[248:249]
	v_pk_mul_f32 v[38:39], v[38:39], v[250:251]
	v_pk_mul_f32 v[20:21], v[20:21], v[248:249]
	v_pk_mul_f32 v[22:23], v[22:23], v[250:251]
	v_mul_f32_e32 v189, v221, v208
	v_fma_f32 v190, s100, v189, v255
	v_fma_f32 v148, v148, v189, -v190
	v_fma_f32 v149, v149, v189, -v190
	v_exp_f32_e32 v148, v148
	v_fma_f32 v150, v150, v189, -v190
	v_exp_f32_e32 v149, v149
	v_fma_f32 v151, v151, v189, -v190
	v_exp_f32_e32 v150, v150
	v_fma_f32 v152, v152, v189, -v190
	v_exp_f32_e32 v151, v151
	v_fma_f32 v153, v153, v189, -v190
	v_exp_f32_e32 v152, v152
	v_fma_f32 v154, v154, v189, -v190
	v_exp_f32_e32 v153, v153
	v_fma_f32 v155, v155, v189, -v190
	v_exp_f32_e32 v154, v154
	v_fma_f32 v156, v156, v189, -v190
	v_exp_f32_e32 v155, v155
	v_fma_f32 v157, v157, v189, -v190
	v_exp_f32_e32 v156, v156
	v_fma_f32 v158, v158, v189, -v190
	v_exp_f32_e32 v157, v157
	v_fma_f32 v159, v159, v189, -v190
	v_exp_f32_e32 v158, v158
	v_fma_f32 v160, v160, v189, -v190
	v_exp_f32_e32 v159, v159
	v_fma_f32 v161, v161, v189, -v190
	v_exp_f32_e32 v160, v160
	v_fma_f32 v162, v162, v189, -v190
	v_exp_f32_e32 v161, v161
	v_fma_f32 v163, v163, v189, -v190
	v_exp_f32_e32 v162, v162
	v_exp_f32_e32 v163, v163
	v_add_f32_e32 v188, v148, v149
	v_add_f32_e32 v189, v150, v151
	v_add_f32_e32 v190, v152, v153
	v_add_f32_e32 v191, v154, v155
	v_add_f32_e32 v192, v156, v157
	v_add_f32_e32 v193, v158, v159
	v_add_f32_e32 v194, v160, v161
	v_add_f32_e32 v195, v162, v163
	v_add_f32_e32 v188, v188, v189
	v_add_f32_e32 v190, v190, v191
	v_add_f32_e32 v192, v192, v193
	v_add_f32_e32 v194, v194, v195
	v_add_f32_e32 v188, v188, v190
	v_add_f32_e32 v192, v192, v194
	v_add_f32_e32 v188, v188, v192
	v_cvt_pk_bf16_f32 v155, v154, v155
	v_cvt_pk_bf16_f32 v154, v152, v153
	v_cvt_pk_bf16_f32 v152, v148, v149
	v_cvt_pk_bf16_f32 v153, v150, v151
	v_cvt_pk_bf16_f32 v148, v156, v157
	v_cvt_pk_bf16_f32 v149, v158, v159
	v_cvt_pk_bf16_f32 v150, v160, v161
	v_cvt_pk_bf16_f32 v151, v162, v163
	s_branch .Lv4_cont_h3
.Lv4_rare_h4:
	ds_read_b128 v[244:247], v225 offset:20480
	ds_read_b128 v[248:251], v226 offset:20480
	s_waitcnt lgkmcnt(1)
	v_mfma_i32_32x32x32_i8 v[148:163], v[244:247], v[164:167], v[132:147]
	ds_read_b128 v[244:247], v227 offset:20480
	s_waitcnt lgkmcnt(1)
	v_mfma_i32_32x32x32_i8 v[148:163], v[248:251], v[168:171], v[148:163]
	ds_read_b128 v[248:251], v228 offset:20480
	s_waitcnt lgkmcnt(1)
	v_mfma_i32_32x32x32_i8 v[148:163], v[244:247], v[172:175], v[148:163]
	s_waitcnt lgkmcnt(0)
	v_mfma_i32_32x32x32_i8 v[148:163], v[248:251], v[176:179], v[148:163]
	s_nop 15
	v_max3_f32 v188, v148, v149, v150
	v_max3_f32 v189, v151, v152, v153
	v_max3_f32 v190, v154, v155, v156
	v_max3_f32 v191, v157, v158, v159
	v_max3_f32 v192, v160, v161, v162
	v_max3_f32 v188, v188, v189, v190
	v_max3_f32 v191, v191, v192, v163
	v_max_f32_e32 v188, v188, v191
	v_add_f32_e32 v188, 0xcb400000, v188
	v_mov_b32_e32 v189, v188
	s_nop 1
	v_permlane32_swap_b32_e32 v188, v189
	v_max_f32_e32 v188, v188, v189
	v_mul_f32_e32 v189, v236, v188
	v_fma_f32 v188, v236, v188, -v237
	v_max_f32_e32 v189, v237, v189
	v_cmp_gt_f32_e32 vcc, v188, v220
	s_nop 1
	v_cndmask_b32_e32 v189, v237, v189, vcc
	v_sub_f32_e32 v188, v237, v189
	v_mul_f32_e32 v188, v221, v188
	v_exp_f32_e32 v254, v188
	v_mov_b32_e32 v237, v189
	v_mul_f32_e32 v255, v221, v189
	v_mul_f32_e32 v224, v224, v254
	s_and_saveexec_b64 vcc, s[0:1]
	ds_write_b32 v223, v254
	s_or_b64 exec, exec, vcc
	s_waitcnt lgkmcnt(0)
	v_add_u32_e32 v253, s78, v218
	ds_read_b128 v[244:247], v253 offset:96
	ds_read_b128 v[248:251], v253 offset:64
	s_waitcnt lgkmcnt(1)
	v_pk_mul_f32 v[16:17], v[16:17], v[244:245]
	v_pk_mul_f32 v[18:19], v[18:19], v[246:247]
	v_pk_mul_f32 v[128:129], v[128:129], v[244:245]
	v_pk_mul_f32 v[130:131], v[130:131], v[246:247]
	v_pk_mul_f32 v[112:113], v[112:113], v[244:245]
	v_pk_mul_f32 v[114:115], v[114:115], v[246:247]
	v_pk_mul_f32 v[96:97], v[96:97], v[244:245]
	v_pk_mul_f32 v[98:99], v[98:99], v[246:247]
	v_pk_mul_f32 v[80:81], v[80:81], v[244:245]
	v_pk_mul_f32 v[82:83], v[82:83], v[246:247]
	v_pk_mul_f32 v[64:65], v[64:65], v[244:245]
	v_pk_mul_f32 v[66:67], v[66:67], v[246:247]
	v_pk_mul_f32 v[48:49], v[48:49], v[244:245]
	v_pk_mul_f32 v[50:51], v[50:51], v[246:247]
	v_pk_mul_f32 v[32:33], v[32:33], v[244:245]
	v_pk_mul_f32 v[34:35], v[34:35], v[246:247]
	s_waitcnt lgkmcnt(0)
	v_pk_mul_f32 v[12:13], v[12:13], v[248:249]
	v_pk_mul_f32 v[14:15], v[14:15], v[250:251]
	v_pk_mul_f32 v[124:125], v[124:125], v[248:249]
	v_pk_mul_f32 v[126:127], v[126:127], v[250:251]
	v_pk_mul_f32 v[108:109], v[108:109], v[248:249]
	v_pk_mul_f32 v[110:111], v[110:111], v[250:251]
	v_pk_mul_f32 v[92:93], v[92:93], v[248:249]
	v_pk_mul_f32 v[94:95], v[94:95], v[250:251]
	v_pk_mul_f32 v[76:77], v[76:77], v[248:249]
	v_pk_mul_f32 v[78:79], v[78:79], v[250:251]
	v_pk_mul_f32 v[60:61], v[60:61], v[248:249]
	v_pk_mul_f32 v[62:63], v[62:63], v[250:251]
	v_pk_mul_f32 v[44:45], v[44:45], v[248:249]
	v_pk_mul_f32 v[46:47], v[46:47], v[250:251]
	v_pk_mul_f32 v[28:29], v[28:29], v[248:249]
	v_pk_mul_f32 v[30:31], v[30:31], v[250:251]
	ds_read_b128 v[244:247], v253 offset:32
	ds_read_b128 v[248:251], v253
	s_waitcnt lgkmcnt(1)
	v_pk_mul_f32 v[8:9], v[8:9], v[244:245]
	v_pk_mul_f32 v[10:11], v[10:11], v[246:247]
	v_pk_mul_f32 v[120:121], v[120:121], v[244:245]
	v_pk_mul_f32 v[122:123], v[122:123], v[246:247]
	v_pk_mul_f32 v[104:105], v[104:105], v[244:245]
	v_pk_mul_f32 v[106:107], v[106:107], v[246:247]
	v_pk_mul_f32 v[88:89], v[88:89], v[244:245]
	v_pk_mul_f32 v[90:91], v[90:91], v[246:247]
	v_pk_mul_f32 v[72:73], v[72:73], v[244:245]
	v_pk_mul_f32 v[74:75], v[74:75], v[246:247]
	v_pk_mul_f32 v[56:57], v[56:57], v[244:245]
	v_pk_mul_f32 v[58:59], v[58:59], v[246:247]
	v_pk_mul_f32 v[40:41], v[40:41], v[244:245]
	v_pk_mul_f32 v[42:43], v[42:43], v[246:247]
	v_pk_mul_f32 v[24:25], v[24:25], v[244:245]
	v_pk_mul_f32 v[26:27], v[26:27], v[246:247]
	s_waitcnt lgkmcnt(0)
	v_pk_mul_f32 v[4:5], v[4:5], v[248:249]
	v_pk_mul_f32 v[6:7], v[6:7], v[250:251]
	v_pk_mul_f32 v[116:117], v[116:117], v[248:249]
	v_pk_mul_f32 v[118:119], v[118:119], v[250:251]
	v_pk_mul_f32 v[100:101], v[100:101], v[248:249]
	v_pk_mul_f32 v[102:103], v[102:103], v[250:251]
	v_pk_mul_f32 v[84:85], v[84:85], v[248:249]
	v_pk_mul_f32 v[86:87], v[86:87], v[250:251]
	v_pk_mul_f32 v[68:69], v[68:69], v[248:249]
	v_pk_mul_f32 v[70:71], v[70:71], v[250:251]
	v_pk_mul_f32 v[52:53], v[52:53], v[248:249]
	v_pk_mul_f32 v[54:55], v[54:55], v[250:251]
	v_pk_mul_f32 v[36:37], v[36:37], v[248:249]
	v_pk_mul_f32 v[38:39], v[38:39], v[250:251]
	v_pk_mul_f32 v[20:21], v[20:21], v[248:249]
	v_pk_mul_f32 v[22:23], v[22:23], v[250:251]
	v_mul_f32_e32 v189, v221, v236
	v_fma_f32 v190, s100, v189, v255
	v_fma_f32 v148, v148, v189, -v190
	v_fma_f32 v149, v149, v189, -v190
	v_exp_f32_e32 v148, v148
	v_fma_f32 v150, v150, v189, -v190
	v_exp_f32_e32 v149, v149
	v_fma_f32 v151, v151, v189, -v190
	v_exp_f32_e32 v150, v150
	v_fma_f32 v152, v152, v189, -v190
	v_exp_f32_e32 v151, v151
	v_fma_f32 v153, v153, v189, -v190
	v_exp_f32_e32 v152, v152
	v_fma_f32 v154, v154, v189, -v190
	v_exp_f32_e32 v153, v153
	v_fma_f32 v155, v155, v189, -v190
	v_exp_f32_e32 v154, v154
	v_fma_f32 v156, v156, v189, -v190
	v_exp_f32_e32 v155, v155
	v_fma_f32 v157, v157, v189, -v190
	v_exp_f32_e32 v156, v156
	v_fma_f32 v158, v158, v189, -v190
	v_exp_f32_e32 v157, v157
	v_fma_f32 v159, v159, v189, -v190
	v_exp_f32_e32 v158, v158
	v_fma_f32 v160, v160, v189, -v190
	v_exp_f32_e32 v159, v159
	v_fma_f32 v161, v161, v189, -v190
	v_exp_f32_e32 v160, v160
	v_fma_f32 v162, v162, v189, -v190
	v_exp_f32_e32 v161, v161
	v_fma_f32 v163, v163, v189, -v190
	v_exp_f32_e32 v162, v162
	v_exp_f32_e32 v163, v163
	v_add_f32_e32 v188, v148, v149
	v_add_f32_e32 v189, v150, v151
	v_add_f32_e32 v190, v152, v153
	v_add_f32_e32 v191, v154, v155
	v_add_f32_e32 v192, v156, v157
	v_add_f32_e32 v193, v158, v159
	v_add_f32_e32 v194, v160, v161
	v_add_f32_e32 v195, v162, v163
	v_add_f32_e32 v188, v188, v189
	v_add_f32_e32 v190, v190, v191
	v_add_f32_e32 v192, v192, v193
	v_add_f32_e32 v194, v194, v195
	v_add_f32_e32 v188, v188, v190
	v_add_f32_e32 v192, v192, v194
	v_add_f32_e32 v188, v188, v192
	v_cvt_pk_bf16_f32 v155, v154, v155
	v_cvt_pk_bf16_f32 v154, v152, v153
	v_cvt_pk_bf16_f32 v152, v148, v149
	v_cvt_pk_bf16_f32 v153, v150, v151
	v_cvt_pk_bf16_f32 v148, v156, v157
	v_cvt_pk_bf16_f32 v149, v158, v159
	v_cvt_pk_bf16_f32 v150, v160, v161
	v_cvt_pk_bf16_f32 v151, v162, v163
	s_branch .Lv4_cont_h4

.Lb4_mid:
	s_barrier
	s_setprio 1
	s_waitcnt vmcnt(0)
	global_load_dwordx2 v[208:209], v201, s[2:3]
	s_cselect_b32 s85, s21, s77
	s_cselect_b32 s88, s20, s76
	s_lshl_b64 s[2:3], s[4:5], 9
	s_add_u32 s2, s88, s2
	ds_read_b128 v[180:183], v225
	ds_read_b128 v[184:187], v226
	s_addc_u32 s3, s85, s3
	s_cmp_lg_u32 0, -1
	s_cselect_b32 s4, 0, 0
	s_add_i32 s85, s4, s80
	s_add_i32 s4, s4, s81
	s_addk_i32 s85, 0x4000
	s_add_i32 s88, s4, 0x10000
	s_waitcnt lgkmcnt(1)
	v_mfma_i32_32x32x32_i8 v[148:163], v[180:183], v[164:167], v[132:147]
	ds_read_b128 v[180:183], v227
	s_waitcnt lgkmcnt(1)
	v_mfma_i32_32x32x32_i8 v[148:163], v[184:187], v[168:171], v[148:163]
	ds_read_b128 v[188:191], v228
	s_waitcnt lgkmcnt(1)
	v_mfma_i32_32x32x32_i8 v[148:163], v[180:183], v[172:175], v[148:163]
	ds_read_b64_tr_b16 v[184:185], v3 offset:32768
	ds_read_b64_tr_b16 v[186:187], v3 offset:36864
	s_waitcnt lgkmcnt(2)
	v_mfma_i32_32x32x32_i8 v[148:163], v[188:191], v[176:179], v[148:163]
	ds_read_b64_tr_b16 v[180:181], v3 offset:33280
	ds_read_b64_tr_b16 v[182:183], v3 offset:37376
	s_nop 7
	v_mul_f32_e32 v189, v221, v206
	v_fma_f32 v190, s100, v189, v255
	v_fma_f32 v148, v148, v189, -v190
	v_fma_f32 v149, v149, v189, -v190
	v_exp_f32_e32 v148, v148
	v_fma_f32 v150, v150, v189, -v190
	v_exp_f32_e32 v149, v149
	v_fma_f32 v151, v151, v189, -v190
	v_exp_f32_e32 v150, v150
	v_fma_f32 v152, v152, v189, -v190
	v_exp_f32_e32 v151, v151
	v_fma_f32 v153, v153, v189, -v190
	v_exp_f32_e32 v152, v152
	v_fma_f32 v154, v154, v189, -v190
	v_exp_f32_e32 v153, v153
	v_fma_f32 v155, v155, v189, -v190
	v_exp_f32_e32 v154, v154
	v_fma_f32 v156, v156, v189, -v190
	v_exp_f32_e32 v155, v155
	v_fma_f32 v157, v157, v189, -v190
	v_exp_f32_e32 v156, v156
	v_fma_f32 v158, v158, v189, -v190
	v_exp_f32_e32 v157, v157
	v_fma_f32 v159, v159, v189, -v190
	v_exp_f32_e32 v158, v158
	v_fma_f32 v160, v160, v189, -v190
	v_exp_f32_e32 v159, v159
	v_fma_f32 v161, v161, v189, -v190
	v_exp_f32_e32 v160, v160
	v_fma_f32 v162, v162, v189, -v190
	v_exp_f32_e32 v161, v161
	v_fma_f32 v163, v163, v189, -v190
	v_exp_f32_e32 v162, v162
	v_exp_f32_e32 v163, v163
	v_add_f32_e32 v188, v148, v149
	v_add_f32_e32 v189, v150, v151
	v_add_f32_e32 v190, v152, v153
	v_add_f32_e32 v191, v154, v155
	v_add_f32_e32 v192, v156, v157
	v_add_f32_e32 v193, v158, v159
	v_add_f32_e32 v194, v160, v161
	v_add_f32_e32 v195, v162, v163
	v_add_f32_e32 v188, v188, v189
	v_add_f32_e32 v190, v190, v191
	v_add_f32_e32 v192, v192, v193
	v_add_f32_e32 v194, v194, v195
	v_add_f32_e32 v188, v188, v190
	v_add_f32_e32 v192, v192, v194
	v_add_f32_e32 v188, v188, v192
	v_cmp_lt_f32_e32 vcc, s101, v188
	v_cvt_pk_bf16_f32 v155, v154, v155
	v_cvt_pk_bf16_f32 v154, v152, v153
	v_cvt_pk_bf16_f32 v152, v148, v149
	v_cvt_pk_bf16_f32 v153, v150, v151
	v_cvt_pk_bf16_f32 v148, v156, v157
	v_cvt_pk_bf16_f32 v149, v158, v159
	v_cvt_pk_bf16_f32 v150, v160, v161
	v_cvt_pk_bf16_f32 v151, v162, v163
	s_cbranch_vccnz .Lb5_rare_h1

.Lb5_cont_h2:
	v_add_f32_e32 v224, v224, v188
	s_min_u32 s85, s79, s84
	s_lshl_b32 s4, s85, 6
	s_cmp_lt_u32 s85, 4
	s_cselect_b64 s[2:3], -1, 0
	s_add_i32 s88, s4, 0xffffff00
	s_and_b64 s[86:87], s[2:3], exec
	s_cselect_b32 s4, s4, s88
	s_cselect_b32 s88, s17, s73
	s_cselect_b32 s89, s16, s72
	s_lshl_b64 s[86:87], s[4:5], 7
	s_add_u32 s86, s89, s86
	s_addc_u32 s87, s88, s87
	s_lshl_b32 s88, s85, 1
	s_mov_b32 s89, s5
	s_lshl_b64 s[88:89], s[88:89], 2
	s_add_u32 s85, s18, s88
	s_addc_u32 s90, s19, s89
	s_add_u32 s88, s74, s88
	s_addc_u32 s89, s75, s89
	s_add_u32 s88, s88, 0xffffffe0
	s_addc_u32 s89, s89, -1
	s_and_b64 s[2:3], s[2:3], exec
	s_waitcnt vmcnt(0)
	v_mov_b32_e32 v236, v209
	s_cselect_b32 s3, s90, s89
	s_cselect_b32 s2, s85, s88
	s_waitcnt vmcnt(0) lgkmcnt(0)
	s_barrier
	s_setprio 0
	s_waitcnt lgkmcnt(2)
	v_mfma_f32_32x32x16_bf16 v[4:19], v[152:155], v[184:187], v[4:19]
	ds_read_b64_tr_b16 v[156:157], v3 offset:50176
	ds_read_b64_tr_b16 v[158:159], v3 offset:54272
	s_waitcnt lgkmcnt(2)
	v_mfma_f32_32x32x16_bf16 v[116:131], v[152:155], v[180:183], v[116:131]
	ds_read_b64_tr_b16 v[160:161], v3 offset:50688
	ds_read_b64_tr_b16 v[162:163], v3 offset:54784
	s_waitcnt lgkmcnt(2)
	v_mfma_f32_32x32x16_bf16 v[100:115], v[152:155], v[156:159], v[100:115]
	ds_read_b64_tr_b16 v[156:157], v3 offset:51200
	ds_read_b64_tr_b16 v[158:159], v3 offset:55296
	s_waitcnt lgkmcnt(2)
	v_mfma_f32_32x32x16_bf16 v[84:99], v[152:155], v[160:163], v[84:99]
	ds_read_b64_tr_b16 v[160:161], v3 offset:51712
	ds_read_b64_tr_b16 v[162:163], v3 offset:55808
	s_waitcnt lgkmcnt(2)
	v_mfma_f32_32x32x16_bf16 v[68:83], v[152:155], v[156:159], v[68:83]
	ds_read_b64_tr_b16 v[156:157], v3 offset:52224
	ds_read_b64_tr_b16 v[158:159], v3 offset:56320
	s_waitcnt lgkmcnt(2)
	v_mfma_f32_32x32x16_bf16 v[52:67], v[152:155], v[160:163], v[52:67]
	ds_read_b64_tr_b16 v[160:161], v3 offset:52736
	ds_read_b64_tr_b16 v[162:163], v3 offset:56832
	s_waitcnt lgkmcnt(2)
	v_mfma_f32_32x32x16_bf16 v[36:51], v[152:155], v[156:159], v[36:51]
	ds_read_b64_tr_b16 v[156:157], v3 offset:57344
	ds_read_b64_tr_b16 v[158:159], v3 offset:61440
	s_waitcnt lgkmcnt(2)
	v_mfma_f32_32x32x16_bf16 v[20:35], v[152:155], v[160:163], v[20:35]
	ds_read_b64_tr_b16 v[152:153], v3 offset:57856
	ds_read_b64_tr_b16 v[154:155], v3 offset:61952
	s_waitcnt lgkmcnt(2)
	v_mfma_f32_32x32x16_bf16 v[4:19], v[148:151], v[156:159], v[4:19]
	ds_read_b64_tr_b16 v[156:157], v3 offset:58368
	ds_read_b64_tr_b16 v[158:159], v3 offset:62464
	s_waitcnt lgkmcnt(2)
	v_mfma_f32_32x32x16_bf16 v[116:131], v[148:151], v[152:155], v[116:131]
	ds_read_b64_tr_b16 v[152:153], v3 offset:58880
	ds_read_b64_tr_b16 v[154:155], v3 offset:62976
	s_waitcnt lgkmcnt(2)
	v_mfma_f32_32x32x16_bf16 v[100:115], v[148:151], v[156:159], v[100:115]
	ds_read_b64_tr_b16 v[156:157], v3 offset:59392
	ds_read_b64_tr_b16 v[158:159], v3 offset:63488
	s_waitcnt lgkmcnt(2)
	v_mfma_f32_32x32x16_bf16 v[84:99], v[148:151], v[152:155], v[84:99]
	ds_read_b64_tr_b16 v[152:153], v3 offset:59904
	ds_read_b64_tr_b16 v[154:155], v3 offset:64000
	s_waitcnt lgkmcnt(2)
	v_mfma_f32_32x32x16_bf16 v[68:83], v[148:151], v[156:159], v[68:83]
	ds_read_b64_tr_b16 v[156:157], v3 offset:60416
	ds_read_b64_tr_b16 v[158:159], v3 offset:64512
	s_waitcnt lgkmcnt(2)
	v_mfma_f32_32x32x16_bf16 v[52:67], v[148:151], v[152:155], v[52:67]
	ds_read_b64_tr_b16 v[152:153], v3 offset:60928
	ds_read_b64_tr_b16 v[154:155], v3 offset:65024
	s_waitcnt lgkmcnt(2)
	v_mfma_f32_32x32x16_bf16 v[36:51], v[148:151], v[156:159], v[36:51]
	s_waitcnt lgkmcnt(0)
	v_mfma_f32_32x32x16_bf16 v[20:35], v[148:151], v[152:155], v[20:35]
	s_barrier
	s_setprio 1
	global_load_dwordx2 v[206:207], v201, s[2:3]
	ds_read_b128 v[180:183], v225 offset:16384
	ds_read_b128 v[184:187], v226 offset:16384
	s_cselect_b32 s85, s21, s77
	s_cselect_b32 s88, s20, s76
	s_lshl_b64 s[2:3], s[4:5], 9
	s_add_u32 s2, s88, s2
	s_addc_u32 s3, s85, s3
	s_waitcnt lgkmcnt(1)
	v_mfma_i32_32x32x32_i8 v[148:163], v[180:183], v[164:167], v[132:147]
	ds_read_b128 v[180:183], v227 offset:16384
	s_waitcnt lgkmcnt(1)
	v_mfma_i32_32x32x32_i8 v[148:163], v[184:187], v[168:171], v[148:163]
	ds_read_b128 v[188:191], v228 offset:16384
	s_waitcnt lgkmcnt(1)
	v_mfma_i32_32x32x32_i8 v[148:163], v[180:183], v[172:175], v[148:163]
	ds_read_b64_tr_b16 v[184:185], v222 offset:32768
	ds_read_b64_tr_b16 v[186:187], v222 offset:36864
	s_waitcnt lgkmcnt(2)
	v_mfma_i32_32x32x32_i8 v[148:163], v[188:191], v[176:179], v[148:163]
	ds_read_b64_tr_b16 v[180:181], v222 offset:33280
	ds_read_b64_tr_b16 v[182:183], v222 offset:37376
	s_nop 7
	s_mov_b32 s90, s94
	v_mul_f32_e32 v189, v221, v208
	v_fma_f32 v190, s100, v189, v255
	v_fma_f32 v148, v148, v189, -v190
	v_fma_f32 v149, v149, v189, -v190
	v_exp_f32_e32 v148, v148
	v_fma_f32 v150, v150, v189, -v190
	v_exp_f32_e32 v149, v149
	v_fma_f32 v151, v151, v189, -v190
	v_exp_f32_e32 v150, v150
	v_fma_f32 v152, v152, v189, -v190
	v_exp_f32_e32 v151, v151
	v_fma_f32 v153, v153, v189, -v190
	v_exp_f32_e32 v152, v152
	v_fma_f32 v154, v154, v189, -v190
	v_exp_f32_e32 v153, v153
	v_fma_f32 v155, v155, v189, -v190
	v_exp_f32_e32 v154, v154
	v_fma_f32 v156, v156, v189, -v190
	v_exp_f32_e32 v155, v155
	v_fma_f32 v157, v157, v189, -v190
	v_exp_f32_e32 v156, v156
	v_fma_f32 v158, v158, v189, -v190
	v_exp_f32_e32 v157, v157
	v_fma_f32 v159, v159, v189, -v190
	v_exp_f32_e32 v158, v158
	v_fma_f32 v160, v160, v189, -v190
	v_exp_f32_e32 v159, v159
	v_fma_f32 v161, v161, v189, -v190
	v_exp_f32_e32 v160, v160
	v_fma_f32 v162, v162, v189, -v190
	v_exp_f32_e32 v161, v161
	v_fma_f32 v163, v163, v189, -v190
	v_exp_f32_e32 v162, v162
	v_exp_f32_e32 v163, v163
	v_add_f32_e32 v188, v148, v149
	v_add_f32_e32 v189, v150, v151
	v_add_f32_e32 v190, v152, v153
	v_add_f32_e32 v191, v154, v155
	v_add_f32_e32 v192, v156, v157
	v_add_f32_e32 v193, v158, v159
	v_add_f32_e32 v194, v160, v161
	v_add_f32_e32 v195, v162, v163
	v_add_f32_e32 v188, v188, v189
	v_add_f32_e32 v190, v190, v191
	v_add_f32_e32 v192, v192, v193
	v_add_f32_e32 v194, v194, v195
	v_add_f32_e32 v188, v188, v190
	v_add_f32_e32 v192, v192, v194
	v_add_f32_e32 v188, v188, v192
	v_cmp_lt_f32_e32 vcc, s101, v188
	v_cvt_pk_bf16_f32 v155, v154, v155
	v_cvt_pk_bf16_f32 v154, v152, v153
	v_cvt_pk_bf16_f32 v152, v148, v149
	v_cvt_pk_bf16_f32 v153, v150, v151
	v_cvt_pk_bf16_f32 v148, v156, v157
	v_cvt_pk_bf16_f32 v149, v158, v159
	v_cvt_pk_bf16_f32 v150, v160, v161
	v_cvt_pk_bf16_f32 v151, v162, v163
	s_cbranch_vccnz .Lb5_rare_h3

; __device__ __forceinline__ void attn_unit256q(const bf16* __restrict__ Qb, const unsigned char* __restrict__ Kc, const unsigned char* __restrict__ Kl, const float* __restrict__ Sc, const float* __restrict__ Sl, ...
;     ...
;   for (int j = 0; j < NT; j += 2) {
;     A5_TILE(0, 0, KBUF, VBUF, j);
;     A5_TILE(KBUF, VBUF, 0, 0, j + 1);
;   }
.Lb5_cont_h4:
	v_add_f32_e32 v224, v224, v188
	s_add_i32 s2, s79, 2
	s_cmp_ge_u32 s79, s70
	s_cbranch_scc1 .Lb4_exit
	s_mov_b32 s79, s2
	s_branch .Lb4_loop
